# combo12 + pool: the t0-1 history row load of each item also issued up front
# speedup vs baseline: 1.0094x; 1.0094x over previous
; __device__ __forceinline__ float bf2f(short b) { return __uint_as_float(((unsigned)(unsigned short)b) << 16); }
; template <int W>
; __device__ __forceinline__ void pool_item(const Params& p, const bf16_t* __restrict__ U, bf16_t* __restrict__ PO, bool samp, int b, int rowb, int t0, int c4) {
;     ...
;     f32x4 r[W + NR - 1];
; #pragma unroll
;     for (int j = 0; j < W + NR - 1; ++j) {
;         const int tp = t0 - W + 1 + j;
;         if (tp >= 0) { const bf16x4 v = *(const bf16x4*)(U + (size_t)(rowb + tp) * DM + c4); r[j] = (f32x4){bf2f(v[0]), bf2f(v[1]), bf2f(v[2]), bf2f(v[3])}; }
;         else if (samp) r[j] = *(const f32x4*)(hist + (size_t)(15 + tp) * 1024 + c4);
;         else r[j] = (f32x4){0.f, 0.f, 0.f, 0.f};
;     }
; __device__ __forceinline__ void phase_pool(const Params& p) {
;     const bf16_t* U = (const bf16_t*)(p.ws + WS_U);
;     bf16_t* PO = (bf16_t*)(p.ws + WS_POOL);
;     const int nthr = gridDim.x * 512;
;     for (int idx = blockIdx.x * 512 + threadIdx.x; idx < 2112 * 256; idx += nthr) {
;         const int c4 = (idx & 255) * 4, rg = idx >> 8;
;         const bool samp = rg >= 2048;
;         int b, rowb, t0;
;         if (!samp) { b = rg >> 8; rowb = b * 2048; t0 = (rg & 255) * 8; } else { const int s = rg - 2048; b = s >> 1; rowb = MP + b * 16; t0 = (s & 1) * 8; }
;         const int g = c4 >> 8;
;         if (g == 0) pool_item<2>(p, U, PO, samp, b, rowb, t0, c4);
;         else if (g == 1) pool_item<4>(p, U, PO, samp, b, rowb, t0, c4);
;         else if (g == 2) pool_item<8>(p, U, PO, samp, b, rowb, t0, c4);
;         else pool_item<16>(p, U, PO, samp, b, rowb, t0, c4);
.LBB0_996:
	v_ashrrev_i32_e32 v0, 8, v156
	v_cmp_lt_i32_e64 s[40:41], s30, v0
	v_cmp_gt_i32_e64 s[2:3], s31, v0
	s_and_saveexec_b64 s[0:1], s[2:3]
	s_xor_b64 s[0:1], exec, s[0:1]
	v_ashrrev_i32_e32 v91, 16, v156
	v_lshlrev_b32_e32 v76, 11, v91
	s_or_saveexec_b64 s[0:1], s[0:1]
	s_waitcnt lgkmcnt(0)
	v_mov_b32_e32 v1, 0x7f8
	s_xor_b64 exec, exec, s[0:1]
	v_add_u32_e32 v1, 0xfffff800, v0
	v_lshrrev_b32_e32 v91, 1, v1
	v_lshl_add_u32 v76, v91, 4, v97
	v_mov_b32_e32 v1, 8
	s_or_b64 exec, exec, s[0:1]
	v_and_b32_e32 v60, 0x3fc, v96
	v_lshlrev_b32_e32 v0, 3, v0
	v_and_b32_e32 v101, v1, v0
	v_cmp_lt_u32_e32 vcc, s34, v60
	s_mov_b64 s[4:5], 0
	s_and_saveexec_b64 s[0:1], vcc
	s_xor_b64 s[42:43], exec, s[0:1]
	s_cbranch_execz .LBB0_1059
	v_mov_b64_e32 v[0:1], s[64:65]
	v_lshrrev_b32_e32 v3, 8, v60
	v_lshlrev_b32_e32 v64, 1, v60
	v_mov_b32_e32 v65, v61
	v_mad_i64_i32 v[0:1], s[0:1], v91, s35, v[0:1]
	v_lshlrev_b32_e32 v62, 2, v60
	v_mov_b32_e32 v63, v61
	v_lshl_add_u64 v[66:67], s[10:11], 0, v[64:65]
	v_lshl_add_u64 v[68:69], v[0:1], 0, v[62:63]
	v_cmp_lt_i32_e32 vcc, 1, v3
	s_mov_b64 s[52:53], 0
	s_and_saveexec_b64 s[0:1], vcc
	s_xor_b64 s[46:47], exec, s[0:1]
	s_cbranch_execz .LBB0_1253
	v_cmp_ne_u32_e32 vcc, 2, v3
	s_mov_b64 s[54:55], 0
	s_and_saveexec_b64 s[0:1], vcc
	s_xor_b64 s[52:53], exec, s[0:1]
	s_cbranch_execz .LBB0_1172
	v_add_u32_e32 v214, v101, v76
	v_ashrrev_i32_e32 v215, 31, v214
	v_lshlrev_b64 v[214:215], 11, v[214:215]
	v_lshl_add_u64 v[214:215], v[66:67], 0, v[214:215]
	s_mov_b32 s98, 0xffffe000
	s_mov_b32 s99, -1
	global_load_dwordx2 v[216:217], v[214:215], off offset:-2048
	global_load_dwordx2 v[212:213], v[214:215], off offset:-4096
	v_lshl_add_u64 v[214:215], v[214:215], 0, s[98:99]
	global_load_dwordx2 v[210:211], v[214:215], off offset:2048
	global_load_dwordx2 v[208:209], v[214:215], off
	global_load_dwordx2 v[206:207], v[214:215], off offset:-2048
	global_load_dwordx2 v[204:205], v[214:215], off offset:-4096
	v_lshl_add_u64 v[214:215], v[214:215], 0, s[98:99]
	global_load_dwordx2 v[202:203], v[214:215], off offset:2048
	global_load_dwordx2 v[200:201], v[214:215], off
	global_load_dwordx2 v[198:199], v[214:215], off offset:-2048
	global_load_dwordx2 v[196:197], v[214:215], off offset:-4096
	v_lshl_add_u64 v[214:215], v[214:215], 0, s[98:99]
	global_load_dwordx2 v[194:195], v[214:215], off offset:2048
	global_load_dwordx2 v[192:193], v[214:215], off
	global_load_dwordx2 v[190:191], v[214:215], off offset:-2048
	global_load_dwordx2 v[188:189], v[214:215], off offset:-4096
	v_lshl_add_u64 v[214:215], v[214:215], 0, s[98:99]
	global_load_dwordx2 v[186:187], v[214:215], off offset:2048
	v_cmp_gt_u32_e32 vcc, 15, v101
	s_and_saveexec_b64 s[0:1], vcc
	s_xor_b64 s[0:1], exec, s[0:1]
	s_cbranch_execz .LBB0_1007
	v_mov_b32_e32 v27, 0
	v_mov_b32_e32 v26, 0
	v_mov_b32_e32 v25, 0
	v_mov_b32_e32 v24, 0
	s_and_saveexec_b64 s[4:5], s[40:41]
	s_cbranch_execz .LBB0_1006
	v_lshlrev_b32_e32 v0, 12, v101
	v_mov_b32_e32 v1, v61
	v_lshl_add_u64 v[0:1], v[68:69], 0, v[0:1]
	global_load_dwordx4 v[24:27], v[0:1], off

; __device__ __forceinline__ float bf2f(short b) { return __uint_as_float(((unsigned)(unsigned short)b) << 16); }
; template <int W>
; __device__ __forceinline__ void pool_item(const Params& p, const bf16_t* __restrict__ U, bf16_t* __restrict__ PO, bool samp, int b, int rowb, int t0, int c4) {
;     ...
;     for (int j = 0; j < W + NR - 1; ++j) {
;         const int tp = t0 - W + 1 + j;
;         if (tp >= 0) { const bf16x4 v = *(const bf16x4*)(U + (size_t)(rowb + tp) * DM + c4); r[j] = (f32x4){bf2f(v[0]), bf2f(v[1]), bf2f(v[2]), bf2f(v[3])}; }
;         else if (samp) r[j] = *(const f32x4*)(hist + (size_t)(15 + tp) * 1024 + c4);
;         else r[j] = (f32x4){0.f, 0.f, 0.f, 0.f};
.LBB0_1131:
	s_or_b64 exec, exec, s[0:1]
	v_add_u32_e32 v90, -1, v101
	s_and_saveexec_b64 s[0:1], s[4:5]
	s_xor_b64 s[0:1], exec, s[0:1]
	s_cbranch_execz .LBB0_1133
	v_add_u32_e32 v56, v90, v76
	v_ashrrev_i32_e32 v57, 31, v56
	v_lshlrev_b64 v[56:57], 11, v[56:57]
	v_lshl_add_u64 v[56:57], v[66:67], 0, v[56:57]
	s_waitcnt vmcnt(0)
	v_and_b32_e32 v57, 0xffff0000, v216
	v_and_b32_e32 v59, 0xffff0000, v217
	v_lshlrev_b32_e32 v56, 16, v216
	v_lshlrev_b32_e32 v58, 16, v217

; __device__ __forceinline__ float bf2f(short b) { return __uint_as_float(((unsigned)(unsigned short)b) << 16); }
; template <int W>
; __device__ __forceinline__ void pool_item(const Params& p, const bf16_t* __restrict__ U, bf16_t* __restrict__ PO, bool samp, int b, int rowb, int t0, int c4) {
;     ...
;     f32x4 r[W + NR - 1];
; #pragma unroll
;     for (int j = 0; j < W + NR - 1; ++j) {
;         const int tp = t0 - W + 1 + j;
;         if (tp >= 0) { const bf16x4 v = *(const bf16x4*)(U + (size_t)(rowb + tp) * DM + c4); r[j] = (f32x4){bf2f(v[0]), bf2f(v[1]), bf2f(v[2]), bf2f(v[3])}; }
;         else if (samp) r[j] = *(const f32x4*)(hist + (size_t)(15 + tp) * 1024 + c4);
;         else r[j] = (f32x4){0.f, 0.f, 0.f, 0.f};
;     }
.LBB0_1172:
	s_andn2_saveexec_b64 s[52:53], s[52:53]
	s_cbranch_execz .LBB0_1252
	v_add_u32_e32 v214, v101, v76
	v_ashrrev_i32_e32 v215, 31, v214
	v_lshlrev_b64 v[214:215], 11, v[214:215]
	v_lshl_add_u64 v[214:215], v[66:67], 0, v[214:215]
	s_mov_b32 s98, 0xffffe000
	s_mov_b32 s99, -1
	global_load_dwordx2 v[216:217], v[214:215], off offset:-2048
	global_load_dwordx2 v[212:213], v[214:215], off offset:-4096
	v_lshl_add_u64 v[214:215], v[214:215], 0, s[98:99]
	global_load_dwordx2 v[210:211], v[214:215], off offset:2048
	global_load_dwordx2 v[208:209], v[214:215], off
	global_load_dwordx2 v[206:207], v[214:215], off offset:-2048
	global_load_dwordx2 v[204:205], v[214:215], off offset:-4096
	v_lshl_add_u64 v[214:215], v[214:215], 0, s[98:99]
	global_load_dwordx2 v[202:203], v[214:215], off offset:2048
	v_cmp_ne_u32_e64 s[4:5], 0, v101
	s_and_saveexec_b64 s[0:1], s[4:5]
	s_xor_b64 s[0:1], exec, s[0:1]
	s_cbranch_execz .LBB0_1187
	v_add_u32_e32 v0, v101, v76
	v_ashrrev_i32_e32 v1, 31, v0
	v_lshlrev_b64 v[0:1], 11, v[0:1]
	v_lshl_add_u64 v[0:1], v[66:67], 0, v[0:1]
	v_add_co_u32_e32 v0, vcc, 0xffffd000, v0
	s_nop 1
	v_addc_co_u32_e32 v1, vcc, -1, v1, vcc
	s_waitcnt vmcnt(0)
	v_and_b32_e32 v25, 0xffff0000, v202
	v_and_b32_e32 v27, 0xffff0000, v203
	v_lshlrev_b32_e32 v24, 16, v202
	v_lshlrev_b32_e32 v26, 16, v203
	s_andn2_saveexec_b64 s[0:1], s[0:1]
	s_cbranch_execnz .LBB0_1188

; __device__ __forceinline__ float bf2f(short b) { return __uint_as_float(((unsigned)(unsigned short)b) << 16); }
; template <int W>
; __device__ __forceinline__ void pool_item(const Params& p, const bf16_t* __restrict__ U, bf16_t* __restrict__ PO, bool samp, int b, int rowb, int t0, int c4) {
;     ...
;     for (int j = 0; j < W + NR - 1; ++j) {
;         const int tp = t0 - W + 1 + j;
;         if (tp >= 0) { const bf16x4 v = *(const bf16x4*)(U + (size_t)(rowb + tp) * DM + c4); r[j] = (f32x4){bf2f(v[0]), bf2f(v[1]), bf2f(v[2]), bf2f(v[3])}; }
;         else if (samp) r[j] = *(const f32x4*)(hist + (size_t)(15 + tp) * 1024 + c4);
;         else r[j] = (f32x4){0.f, 0.f, 0.f, 0.f};
.LBB0_1211:
	s_or_b64 exec, exec, s[0:1]
	v_add_u32_e32 v70, -1, v101
	s_and_saveexec_b64 s[0:1], s[4:5]
	s_xor_b64 s[0:1], exec, s[0:1]
	s_cbranch_execz .LBB0_1213
	v_add_u32_e32 v4, v70, v76
	v_ashrrev_i32_e32 v5, 31, v4
	v_lshlrev_b64 v[4:5], 11, v[4:5]
	v_lshl_add_u64 v[4:5], v[66:67], 0, v[4:5]
	s_waitcnt vmcnt(0)
	v_and_b32_e32 v5, 0xffff0000, v216
	v_and_b32_e32 v7, 0xffff0000, v217
	v_lshlrev_b32_e32 v4, 16, v216
	v_lshlrev_b32_e32 v6, 16, v217

; __device__ __forceinline__ float bf2f(short b) { return __uint_as_float(((unsigned)(unsigned short)b) << 16); }
; template <int W>
; __device__ __forceinline__ void pool_item(const Params& p, const bf16_t* __restrict__ U, bf16_t* __restrict__ PO, bool samp, int b, int rowb, int t0, int c4) {
;     ...
;     f32x4 r[W + NR - 1];
; #pragma unroll
;     for (int j = 0; j < W + NR - 1; ++j) {
;         const int tp = t0 - W + 1 + j;
;         if (tp >= 0) { const bf16x4 v = *(const bf16x4*)(U + (size_t)(rowb + tp) * DM + c4); r[j] = (f32x4){bf2f(v[0]), bf2f(v[1]), bf2f(v[2]), bf2f(v[3])}; }
;         else if (samp) r[j] = *(const f32x4*)(hist + (size_t)(15 + tp) * 1024 + c4);
;         else r[j] = (f32x4){0.f, 0.f, 0.f, 0.f};
;     }
.LBB0_1253:
	s_andn2_saveexec_b64 s[46:47], s[46:47]
	s_cbranch_execz .LBB0_1307
	v_add_u32_e32 v214, v101, v76
	v_ashrrev_i32_e32 v215, 31, v214
	v_lshlrev_b64 v[214:215], 11, v[214:215]
	v_lshl_add_u64 v[214:215], v[66:67], 0, v[214:215]
	s_mov_b32 s98, 0xffffe000
	s_mov_b32 s99, -1
	global_load_dwordx2 v[216:217], v[214:215], off offset:-2048
	global_load_dwordx2 v[212:213], v[214:215], off offset:-4096
	v_lshl_add_u64 v[214:215], v[214:215], 0, s[98:99]
	global_load_dwordx2 v[210:211], v[214:215], off offset:2048
	v_cmp_ne_u32_e64 s[4:5], 0, v101
	s_and_saveexec_b64 s[0:1], s[4:5]
	s_xor_b64 s[0:1], exec, s[0:1]
	s_cbranch_execz .LBB0_1258
	v_add_u32_e32 v0, v101, v76
	v_ashrrev_i32_e32 v1, 31, v0
	v_lshlrev_b64 v[0:1], 11, v[0:1]
	v_lshl_add_u64 v[0:1], v[66:67], 0, v[0:1]
	v_add_co_u32_e32 v0, vcc, 0xfffff000, v0
	s_nop 1
	v_addc_co_u32_e32 v1, vcc, -1, v1, vcc
	s_waitcnt vmcnt(0)
	v_and_b32_e32 v9, 0xffff0000, v210
	v_and_b32_e32 v11, 0xffff0000, v211
	v_lshlrev_b32_e32 v8, 16, v210
	v_lshlrev_b32_e32 v10, 16, v211
	s_andn2_saveexec_b64 s[0:1], s[0:1]
	s_cbranch_execnz .LBB0_1259

; __device__ __forceinline__ float bf2f(short b) { return __uint_as_float(((unsigned)(unsigned short)b) << 16); }
; template <int W>
; __device__ __forceinline__ void pool_item(const Params& p, const bf16_t* __restrict__ U, bf16_t* __restrict__ PO, bool samp, int b, int rowb, int t0, int c4) {
;     ...
;     for (int j = 0; j < W + NR - 1; ++j) {
;         const int tp = t0 - W + 1 + j;
;         if (tp >= 0) { const bf16x4 v = *(const bf16x4*)(U + (size_t)(rowb + tp) * DM + c4); r[j] = (f32x4){bf2f(v[0]), bf2f(v[1]), bf2f(v[2]), bf2f(v[3])}; }
;         else if (samp) r[j] = *(const f32x4*)(hist + (size_t)(15 + tp) * 1024 + c4);
;         else r[j] = (f32x4){0.f, 0.f, 0.f, 0.f};
.LBB0_1266:
	s_or_b64 exec, exec, s[0:1]
	v_add_u32_e32 v16, -1, v101
	s_and_saveexec_b64 s[0:1], s[4:5]
	s_xor_b64 s[0:1], exec, s[0:1]
	s_cbranch_execz .LBB0_1268
	v_add_u32_e32 v0, v16, v76
	v_ashrrev_i32_e32 v1, 31, v0
	v_lshlrev_b64 v[0:1], 11, v[0:1]
	v_lshl_add_u64 v[0:1], v[66:67], 0, v[0:1]
	s_waitcnt vmcnt(0)
	v_and_b32_e32 v1, 0xffff0000, v216
	v_and_b32_e32 v3, 0xffff0000, v217
	v_lshlrev_b32_e32 v0, 16, v216
	v_lshlrev_b32_e32 v2, 16, v217
